# arbitration balance: workgroups with bid >= 256 hold user priority 1 for the first 24 of 48 K-iterations of phase 8 and the first 12 of phase 2 (measured: priority flips which CU-mate is ~7 us slower)
# baseline (speedup 1.0000x reference)
.LBB0_232:
.LBB0_233:
	s_ashr_i32 s2, s76, 3
	s_and_b32 s0, s2, 31
	s_lshr_b32 s1, s2, 5
	s_xor_b32 s1, s1, 1
	s_lshl_b32 s1, s1, 3
	s_and_b32 s2, s0, 7
	s_or_b32 s2, s2, s1
	s_lshr_b32 s0, s0, 3
	s_lshl_b32 s0, s0, 4
	s_or_b32 s2, s2, s0
	s_cmpk_gt_i32 s2, 0xbf
	s_cbranch_scc1 .LBB0_311
	s_mov_b32 s99, 0x10000
	s_cmpk_lt_u32 s76, 0x100
	s_cbranch_scc1 .Lpf_skip_2
	s_movk_i32 s99, 12
	s_setprio 1
.Lpf_skip_2:
	s_lshl_b32 s0, s76, 3
	s_and_b32 s24, s0, 56
	s_ashr_i32 s25, s42, 3
	s_add_u32 s6, s58, 0xcd1000
	s_addc_u32 s7, s59, 0
	s_add_u32 s8, s58, 0x2cd1000
	s_addc_u32 s9, s59, 0
	s_add_u32 s10, s58, 0x8cd1000
	s_addc_u32 s11, s59, 0
	s_add_u32 s28, s58, 0xbd0000
	v_mbcnt_lo_u32_b32 v0, -1, 0
	s_addc_u32 s29, s59, 0
	v_mov_b32_e32 v161, 0
	s_mov_b32 s33, 0x10000
	s_mov_b32 s31, 0
	s_mov_b32 s37, 0x20000
	s_mov_b32 s39, 0x30000
	s_mov_b32 s66, 0x40000
	s_mov_b32 s67, 0x50000
	s_mov_b32 s68, 0x60000
	s_mov_b32 s69, 0x70000
	s_movk_i32 s77, 0x3ff
	s_movk_i32 s78, 0x5ff
	s_movk_i32 s79, 0xfe00
	s_movk_i32 s80, 0x1800
	s_mov_b64 s[34:35], 0x80
	s_movk_i32 s81, 0x1ff
	s_mov_b32 s36, 0x3c800000
	s_mov_b32 s38, 0x358637bd
	s_mov_b32 s82, 0x800000
	v_mbcnt_hi_u32_b32 v186, -1, v0
	s_branch .LBB0_237

.LBB0_238:
	s_add_i32 s99, s99, -1
	s_cmp_eq_u32 s99, 0
	s_cbranch_scc0 .Lpf_on_2
	s_setprio 0

.LBB0_311:
	s_setprio 0
	s_waitcnt vmcnt(0)
	v_readlane_b32 s0, v255, 1
	v_readlane_b32 s1, v255, 2
	s_waitcnt lgkmcnt(0)
	s_barrier
	s_and_saveexec_b64 s[4:5], s[0:1]
	s_cbranch_execz .LBB0_363
	s_mov_b64 s[98:99], s[94:95]
	s_lshl_b32 s0, s3, 8
	s_add_u32 s100, s98, s0
	s_addc_u32 s101, s99, 0
	v_mov_b32_e32 v19, 0x10000
	s_waitcnt vmcnt(0) expcnt(0) lgkmcnt(0)
	ds_read_b32 v2, v19
	v_mov_b32_e32 v19, 0x10004
	ds_read_b32 v5, v19
	v_mov_b32_e32 v3, 0x1000
	v_mov_b32_e32 v4, 1
	global_atomic_add v3, v3, v4, s[100:101] offset:1024 sc0
	s_waitcnt vmcnt(0) lgkmcnt(0)
	v_add_u32_e32 v3, 1, v3
	v_mul_u32_u24_e32 v6, 2, v2
	v_add_u32_e32 v6, 1, v6
	v_cmp_eq_u32_e32 vcc, v3, v6
	s_cbranch_vccz .Lgb2_nf
	buffer_wbl2 sc1

.LBB0_1429:
.LBB0_1430:
	s_ashr_i32 s2, s76, 3
	s_cmpk_gt_i32 s2, 0xbf
	s_cbranch_scc1 .LBB0_1959
	s_mov_b32 s99, 0x10000
	s_cmpk_lt_u32 s76, 0x100
	s_cbranch_scc1 .Lpf_skip_8
	s_movk_i32 s99, 24
	s_setprio 1
.Lpf_skip_8:
	s_lshl_b32 s0, s76, 3
	s_and_b32 s22, s0, 56
	s_ashr_i32 s23, s42, 3
	s_add_u32 s4, s58, 0xcd1000
	s_addc_u32 s5, s59, 0
	s_add_u32 s6, s58, 0x2cd1000
	s_addc_u32 s7, s59, 0
	s_add_u32 s8, s58, 0xacd1000
	s_addc_u32 s9, s59, 0
	s_add_u32 s10, s58, 0x8cd1000
	v_mbcnt_lo_u32_b32 v0, -1, 0
	s_addc_u32 s11, s59, 0
	v_mov_b32_e32 v129, 0
	s_mov_b32 s24, 0x10000
	s_mov_b32 s15, 0
	s_mov_b32 s25, 0x20000
	s_mov_b32 s26, 0x30000
	s_mov_b32 s27, 0x40000
	s_mov_b32 s28, 0x50000
	s_mov_b32 s29, 0x60000
	s_mov_b32 s30, 0x70000
	s_movk_i32 s31, 0x400
	s_movk_i32 s33, 0x3ff
	s_movk_i32 s34, 0x1800
	s_movk_i32 s35, 0xf80
	s_mov_b64 s[16:17], 0x80
	v_mbcnt_hi_u32_b32 v138, -1, v0
	s_branch .LBB0_1434

.LBB0_1959:
	s_setprio 0
	s_waitcnt vmcnt(0)
	s_waitcnt vmcnt(63) expcnt(7) lgkmcnt(15)
	s_barrier
	s_mov_b64 s[4:5], exec
	v_readlane_b32 s0, v255, 1
	v_readlane_b32 s1, v255, 2
	s_and_b64 s[0:1], s[4:5], s[0:1]
	s_mov_b64 exec, s[0:1]
	s_cbranch_execz .LBB0_2011
	v_mov_b32_e32 v0, 0x10000
	s_waitcnt vmcnt(0) expcnt(0) lgkmcnt(0)
	ds_read_b32 v2, v0
	v_mov_b32_e32 v0, 0x10004
	ds_read_b32 v0, v0
	s_waitcnt lgkmcnt(1)
	v_cmp_ne_u32_e32 vcc, 0, v2
	s_cbranch_vccnz .LBB0_1975
	s_add_u32 s6, s58, 0xfd29200
	s_addc_u32 s7, s59, 0
	s_add_u32 s8, s58, 0xfd29400
	s_addc_u32 s9, s59, 0
	s_add_u32 s10, s58, 0xfd29500
	s_addc_u32 s11, s59, 0
	s_add_u32 s14, s58, 0xfd29600
	s_addc_u32 s15, s59, 0
	s_add_u32 s16, s58, 0xfd29700
	s_addc_u32 s17, s59, 0
	s_add_u32 s18, s58, 0xfd29800
	s_addc_u32 s19, s59, 0
	s_add_u32 s20, s58, 0xfd29900
	s_addc_u32 s21, s59, 0
	s_add_u32 s22, s58, 0xfd29a00
	s_addc_u32 s23, s59, 0
	s_add_u32 s24, s58, 0xfd29b00
	s_addc_u32 s25, s59, 0
	s_add_u32 s26, s58, 0xfd29c00
	s_addc_u32 s27, s59, 0
	s_add_u32 s28, s58, 0xfd29d00
	s_addc_u32 s29, s59, 0
	s_add_u32 s30, s58, 0xfd29e00
	s_addc_u32 s31, s59, 0
	s_add_u32 s34, s58, 0xfd29f00
	s_addc_u32 s35, s59, 0
	s_add_u32 s36, s58, 0xfd2a000
	s_addc_u32 s37, s59, 0
	s_add_u32 s40, s58, 0xfd2a100
	s_addc_u32 s41, s59, 0
	s_add_u32 s44, s58, 0xfd2a200
	v_readlane_b32 s0, v255, 0
	s_addc_u32 s45, s59, 0
	s_mul_i32 s2, s43, s0
	s_add_u32 s46, s58, 0xfd2a300
	s_mul_i32 s2, s2, s42
	s_addc_u32 s47, s59, 0
	s_mov_b32 s33, 1
	v_mov_b32_e32 v16, 0
	s_branch .LBB0_1963
